# one static s_setprio 1 for waves 4-7 during dsa_attn (two same-program waves per SIMD), on top of attn store widening, f32-MFMA xa_pass, dsa_topk changes
# speedup vs baseline: 1.0176x; 1.0010x over previous
; #define LAS __attribute__((address_space(3)))
; __device__ __forceinline__ void dsa_attn(const bf16_t* DP, const int* SEL, bf16_t* O, LAS unsigned char* lds, int widk) {
;     IDX_SETUP
;     LAS unsigned char* pl = lds + wid * 10240;
;     LAS unsigned char* vt = lds + wid * 10240 + 2048;
;     const int fr = lane & 15, fq = lane >> 4;
;     unsigned tra[8][2];
; #pragma unroll
;     for (int cb = 0; cb < 8; ++cb)
; #pragma unroll
;         for (int t = 0; t < 2; ++t) { const unsigned q_ = (unsigned)(fr >> 2), p_ = (unsigned)(fr & 3), row = 8u * (unsigned)fq + 4u * (unsigned)t + q_, ch = 2u * (unsigned)cb + (p_ >> 1);
;             tra[cb][t] = (unsigned)(size_t)vt + 256u * row + 16u * (ch ^ (((row & 3u) << 2) | ((row >> 2) & 3u))) + 8u * (p_ & 1u); }
;     for (int m = 0;; ++m) {
.LBB0_660:
	s_or_b64 exec, exec, s[0:1]
	v_readlane_b32 s0, v252, 48
	s_waitcnt lgkmcnt(0)
	s_barrier
	v_mbcnt_lo_u32_b32 v2, -1, 0
	v_mbcnt_hi_u32_b32 v2, -1, v2
	s_mov_b32 s4, s41
	v_lshl_or_b32 v0, s0, 6, v2
	s_mov_b32 s1, s33
	v_readfirstlane_b32 s0, v0
	s_ashr_i32 s0, s0, 6
	s_mul_i32 s2, s4, s0
	s_add_i32 s8, s2, s1
	s_cmp_gt_i32 s8, 0xffff
	s_cbranch_scc1 .LBB0_692
	s_cmp_lt_u32 s0, 4
	s_cbranch_scc1 .Lattn_noprio
	s_setprio 1
.Lattn_noprio:
	s_mulk_i32 s0, 0x2800
	s_add_i32 s2, s0, 0
	v_bfe_u32 v6, v2, 4, 2
	s_add_i32 s0, s2, 0x800
	v_bfe_u32 v0, v2, 2, 2
	v_lshlrev_b32_e32 v138, 3, v6
	v_lshlrev_b32_e32 v8, 3, v2
	v_lshrrev_b32_e32 v10, 3, v2
	v_bfe_u32 v4, v2, 1, 1
	v_and_b32_e32 v7, 12, v2
	v_and_or_b32 v8, v8, 8, s0
	v_or_b32_e32 v9, v138, v0
	v_and_b32_e32 v10, 2, v10
	v_or3_b32 v11, v10, v7, v4
	v_lshl_add_u32 v9, v9, 8, v8
	v_lshl_add_u32 v139, v11, 4, v9
	v_or_b32_e32 v11, 4, v138
	v_or_b32_e32 v0, v11, v0
	v_bfe_u32 v11, v11, 2, 2
	v_bitop3_b32 v12, v11, v4, v7 bitop3:0x36
	v_lshl_add_u32 v0, v0, 8, v8
	v_or_b32_e32 v8, 2, v4
	v_lshl_add_u32 v152, v12, 4, v0
	v_bitop3_b32 v12, v10, v8, v7 bitop3:0x36
	v_bitop3_b32 v8, v11, v8, v7 bitop3:0x36
	v_lshl_add_u32 v154, v8, 4, v0
	v_or_b32_e32 v8, 4, v4
	v_lshl_add_u32 v153, v12, 4, v9
	v_bitop3_b32 v12, v10, v8, v7 bitop3:0x36
	v_bitop3_b32 v8, v11, v8, v7 bitop3:0x36
	v_lshl_add_u32 v156, v8, 4, v0
	v_or_b32_e32 v8, 6, v4
	v_lshl_add_u32 v155, v12, 4, v9
	v_bitop3_b32 v12, v10, v8, v7 bitop3:0x36
	v_bitop3_b32 v8, v11, v8, v7 bitop3:0x36
	v_lshl_add_u32 v158, v8, 4, v0
	v_or_b32_e32 v8, 8, v4
	v_lshl_add_u32 v157, v12, 4, v9
	v_bitop3_b32 v12, v10, v8, v7 bitop3:0x36
	v_bitop3_b32 v8, v11, v8, v7 bitop3:0x36
	v_lshl_add_u32 v160, v8, 4, v0
	v_or_b32_e32 v8, 10, v4
	v_lshl_add_u32 v159, v12, 4, v9
	v_bitop3_b32 v12, v10, v8, v7 bitop3:0x36
	v_bitop3_b32 v8, v11, v8, v7 bitop3:0x36
	v_lshl_add_u32 v162, v8, 4, v0
	v_or_b32_e32 v8, 12, v4
	v_lshl_add_u32 v161, v12, 4, v9
	v_bitop3_b32 v12, v10, v8, v7 bitop3:0x36
	v_bitop3_b32 v8, v11, v8, v7 bitop3:0x36
	v_or_b32_e32 v4, 14, v4
	v_and_b32_e32 v3, 63, v2
	v_and_b32_e32 v5, 15, v2
	v_lshl_add_u32 v164, v8, 4, v0
	v_bitop3_b32 v8, v10, v4, v7 bitop3:0x36
	v_bitop3_b32 v4, v11, v4, v7 bitop3:0x36
	v_readlane_b32 s0, v253, 41
	s_and_b32 s5, s8, 3
	v_lshl_add_u32 v166, v4, 4, v0
	v_lshlrev_b32_e32 v0, 2, v3
	v_readlane_b32 s1, v253, 42
	v_lshlrev_b32_e32 v7, 7, v5
	s_lshl_b32 s6, s5, 9
	v_lshl_add_u64 v[140:141], s[0:1], 0, v[0:1]
	v_lshlrev_b32_e32 v167, 2, v6
	v_xor_b32_e32 v169, 64, v0
	v_xor_b32_e32 v170, 0x80, v0
	v_add_lshl_u32 v0, s6, v7, 1
	v_lshl_add_u32 v165, v8, 4, v9
	v_lshl_add_u32 v8, v6, 8, s2
	v_lshl_add_u64 v[6:7], s[44:45], 0, v[0:1]
	v_bitop3_b32 v0, v167, v2, 15 bitop3:0x78
	v_and_b32_e32 v142, 48, v2
	v_lshlrev_b32_e32 v2, 4, v0
	v_bitop3_b32 v0, v167, v5, 1 bitop3:0x36
	v_lshl_add_u32 v171, v5, 9, s2
	v_cmp_gt_u32_e64 s[2:3], 16, v3
	v_mov_b32_e32 v143, v1
	s_lshl_b32 s12, s5, 7
	v_lshlrev_b32_e32 v3, 4, v0
	v_bitop3_b32 v0, v167, v5, 2 bitop3:0x36
	s_lshl_b32 s5, s5, 10
	v_lshl_add_u64 v[144:145], v[6:7], 0, v[142:143]
	v_lshlrev_b32_e32 v6, 4, v0
	v_bitop3_b32 v0, v167, v5, 3 bitop3:0x36
	s_add_u32 s6, s92, s5
	v_lshlrev_b32_e32 v4, 3, v5
	v_lshlrev_b32_e32 v143, 2, v5
	v_lshlrev_b32_e32 v7, 4, v0
	s_addc_u32 s7, s93, 0
	v_lshlrev_b32_e32 v0, 1, v5
	v_lshl_add_u32 v163, v12, 4, v9
	v_cmp_gt_u32_e64 s[0:1], 4, v5
	v_or_b32_e32 v168, 0x80, v167
	v_or_b32_e32 v172, 64, v143
	v_or_b32_e32 v173, 0x80, v143
	v_or_b32_e32 v174, 0xc0, v143
	v_or_b32_e32 v175, 16, v167
	v_or_b32_e32 v176, 32, v167
	v_or_b32_e32 v177, 48, v167
	v_or_b32_e32 v178, 64, v167
	v_or_b32_e32 v179, 0x50, v167
	v_or_b32_e32 v180, 0x60, v167
	v_or_b32_e32 v181, 0x70, v167
	v_or_b32_e32 v182, 0x90, v167
	v_or_b32_e32 v183, 0xa0, v167
	v_or_b32_e32 v184, 0xb0, v167
	v_or_b32_e32 v185, 0xc0, v167
	v_or_b32_e32 v186, 0xd0, v167
	v_or_b32_e32 v187, 0xe0, v167
	v_or_b32_e32 v188, 0xf0, v167
	v_or_b32_e32 v220, 0x92, v167
	v_or_b32_e32 v221, 0x93, v167
	v_or_b32_e32 v222, 0xa1, v167
	v_or_b32_e32 v223, 0xa2, v167
	v_or_b32_e32 v224, 0xa3, v167
	v_or_b32_e32 v225, 0xb1, v167
	v_or_b32_e32 v226, 0xb2, v167
	v_or_b32_e32 v227, 0xb3, v167
	v_or_b32_e32 v228, 0xc1, v167
	v_or_b32_e32 v229, 0xc2, v167
	v_or_b32_e32 v230, 0xc3, v167
	v_or_b32_e32 v231, 0xd1, v167
	v_or_b32_e32 v232, 0xd2, v167
	v_or_b32_e32 v233, 0xd3, v167
	v_or_b32_e32 v234, 0xe1, v167
	v_or_b32_e32 v235, 0xe2, v167
	v_or_b32_e32 v236, 0xe3, v167
	v_or_b32_e32 v237, 0xf1, v167
	v_or_b32_e32 v238, 0xf2, v167
	v_or_b32_e32 v239, 0xf3, v167
	v_lshl_add_u64 v[146:147], s[6:7], 0, v[0:1]
	s_lshl_b32 s9, s8, 11
	s_lshl_b32 s10, s4, 14
	s_lshl_b32 s11, s4, 3
	s_lshl_b32 s12, s12, 1
	v_lshlrev_b32_e32 v0, 1, v138
	v_lshlrev_b32_e32 v148, 1, v4
	v_add_u32_e32 v249, v8, v2
	v_add_u32_e32 v250, v8, v3
	v_add_u32_e32 v251, v8, v6
	v_add_u32_e32 v240, v8, v7
	s_branch .LBB0_663

; __device__ __forceinline__ void dsa_attn(const bf16_t* DP, const int* SEL, bf16_t* O, LAS unsigned char* lds, int widk) {
;     ...
;     }
; }
.LBB0_691:
	s_setprio 0
	v_mov_b32_e32 v248, 0x3727c5ac
	v_mov_b32_e32 v251, 0x260
	v_mov_b32_e32 v229, 0x3000
